# v44 plus write-through sc1 GEMM epilogue stores, DPP row-op reduction hops in the MLA post pass, and non-leader workgroups polling the cross-XCD release word directly in the grid barrier
# speedup vs baseline: 1.0052x; 1.0023x over previous
.LBB0_828:
	s_or_b64 exec, exec, s[4:5]
	v_cvt_f32_u32_e32 v5, v3
	s_waitcnt vmcnt(0)
	v_readfirstlane_b32 s2, v4
	v_sub_u32_e32 v4, 0, v3
	v_rcp_iflag_f32_e32 v5, v5
	v_add_u32_e32 v6, s2, v0
	v_mul_f32_e32 v5, 0x4f7ffffe, v5
	v_cvt_u32_f32_e32 v5, v5
	v_mul_lo_u32 v0, v4, v5
	v_mul_hi_u32 v0, v5, v0
	v_add_u32_e32 v0, v5, v0
	v_mul_hi_u32 v0, v6, v0
	v_mul_lo_u32 v4, v0, v3
	v_sub_u32_e32 v4, v6, v4
	v_add_u32_e32 v5, 1, v0
	v_cmp_ge_u32_e32 vcc, v4, v3
	s_nop 1
	v_cndmask_b32_e32 v0, v0, v5, vcc
	v_sub_u32_e32 v5, v4, v3
	v_cndmask_b32_e32 v4, v4, v5, vcc
	v_add_u32_e32 v5, 1, v0
	v_cmp_ge_u32_e32 vcc, v4, v3
	v_add_u32_e32 v4, 1, v6
	s_nop 0
	v_cndmask_b32_e32 v0, v0, v5, vcc
	v_mul_lo_u32 v5, v3, v0
	v_add_u32_e32 v3, v5, v3
	v_cmp_ne_u32_e32 vcc, v4, v3
	s_and_saveexec_b64 s[2:3], vcc
	s_xor_b64 s[2:3], exec, s[2:3]
	s_cbranch_execz .LBB0_842
	s_mov_b64 s[6:7], s[82:83]
	s_waitcnt lgkmcnt(0)
	global_load_dword v2, v1, s[6:7] sc1
	s_waitcnt vmcnt(0)
	v_cmp_eq_u32_e32 vcc, v2, v0
	s_and_saveexec_b64 s[4:5], vcc
	s_cbranch_execz .LBB0_841
	s_mov_b32 s24, 1
	s_mov_b64 s[8:9], 0
	s_branch .LBB0_832

.LBB0_859:
	s_or_b64 exec, exec, s[2:3]
	s_mov_b64 s[2:3], exec
	v_mbcnt_lo_u32_b32 v0, s2, 0
	v_mbcnt_hi_u32_b32 v0, s3, v0
	v_cmp_eq_u32_e32 vcc, 0, v0
	s_waitcnt vmcnt(0)
	buffer_inv sc1
	s_and_saveexec_b64 s[4:5], vcc
	s_branch .LBB0_861
	s_add_i32 s80, s21, 0x900
	s_lshl_b64 s[6:7], s[80:81], 2
	s_add_u32 s6, s34, s6
	s_addc_u32 s7, s35, s7
	s_bcnt1_i32_b64 s2, s[2:3]
	v_mov_b32_e32 v0, s2
	global_atomic_add v1, v0, s[6:7]
